# A and B item start: head-table and wfar global loads overlap the first K/V stage DMAs instead of preceding them
# baseline (speedup 1.0000x reference)
; #define LAS __attribute__((address_space(3)))
; #define WAITBAR2() asm volatile("s_waitcnt vmcnt(2) lgkmcnt(0)\n\ts_barrier" ::: "memory")
; #define ISSUE_UP() do { STG_ISSUE(s_iss < sb_end ? s_iss : sb_end, slot_i); ++s_iss; slot_i = slot_i == NSTG - 1 ? 0 : slot_i + 1; } while (0)
; __device__ __forceinline__ void blk_B(int b, int hd, int chunk, const bf16_t* QK, const bf16_t* VT, bf16_t* mixed, LAS unsigned char* lds, const float* tblg, float wfar, float lam, float osc, const float* subln, int tid, int lane, int wave) {
;     const int q = lane & 31, h = lane >> 5, qb = chunk * 8 + wave;
;     LOAD_HEAD_TABLE(8 + hd);
;     const size_t tok0 = (size_t)b * SEQ;
;     const bf16_t* Qp = QK + (tok0 + qb * 32 + q) * 2048 + 1024 + hd * 64 + 8 * h;
;     bf16x8 qf[4];
; #pragma unroll
;     for (int s = 0; s < 4; ++s) qf[s] = *(const bf16x8*)(Qp + 16 * s);
;     const Stage st = make_stage(tid, QK, VT, tok0, 1280 + hd * 64, 512 + hd * 64);
;     LAS unsigned char* sb = lds + SBUF_OFF;
;     const int sb_end = chunk * 4 + 3;
;     int s_iss = 0, slot_i = 0, slot_c = 0;
;     ISSUE_UP(); ISSUE_UP();
;     WAITBAR2();
;     f32x16 oa0 = {}, oa1 = {}, ob0 = {}, ob1 = {}; float la = 0.f, lb = 0.f; bool scaled = false;
;     const LAS unsigned char* tb = LANE_TBL();
.LBB0_333:
	s_and_b32 s27, s28, 3
	s_lshl_b32 s0, s27, 2
	s_add_u32 s0, s95, s0
	s_addc_u32 s1, s7, 0
	global_load_dword v0, v230, s[0:1] offset:2544
	v_readlane_b32 s1, v251, 2
	s_mul_i32 s0, s27, 0x8900
	s_add_u32 s0, s1, s0
	v_readlane_b32 s1, v251, 3
	s_addc_u32 s1, s1, 0
	s_add_u32 s0, s0, 0x44800
	s_addc_u32 s1, s1, 0
	s_mov_b64 s[18:19], exec
	s_and_b64 exec, s[18:19], s[42:43]
	v_lshl_add_u64 v[22:23], v[170:171], 4, s[0:1]
	global_load_dwordx4 v[22:25], v[22:23], off
	s_and_b64 exec, s[18:19], s[44:45]
	v_lshl_add_u64 v[6:7], v[180:181], 4, s[0:1]
	global_load_dwordx4 v[6:9], v[6:7], off
	s_and_b64 exec, s[18:19], s[46:47]
	v_lshl_add_u64 v[10:11], v[182:183], 4, s[0:1]
	global_load_dwordx4 v[10:13], v[10:11], off
	s_and_b64 exec, s[18:19], s[48:49]
	v_lshl_add_u64 v[14:15], v[184:185], 4, s[0:1]
	global_load_dwordx4 v[14:17], v[14:15], off
	s_and_b64 exec, s[18:19], s[50:51]
	s_cbranch_execz .Lattn_b_tskip
	v_lshl_add_u64 v[18:19], v[186:187], 4, s[0:1]
	global_load_dwordx4 v[18:21], v[18:19], off
.Lattn_b_tskip:
	s_mov_b64 exec, s[18:19]
	s_mov_b32 s0, 0xc2fc0000
	s_waitcnt vmcnt(4)
	v_mul_f32_e32 v2, 0x3fb8aa3b, v0
	v_cmp_gt_f32_e32 vcc, s0, v2
	s_and_b64 s[0:1], vcc, exec
	s_cselect_b32 s0, 0xffffffc0, 0
	v_cndmask_b32_e32 v2, 0, v237, vcc
	v_fmac_f32_e32 v2, 0x3fb8aa3b, v0
	v_exp_f32_e32 v0, v2
	s_nop 0
	v_ldexp_f32 v0, v0, s0
	s_nop 1
	v_readfirstlane_b32 s54, v0
.LBB0_353:
	s_ashr_i32 s18, s28, 5
	s_sub_i32 s19, 31, s18
	s_lshl_b32 s29, s19, 3
	s_add_i32 s29, s29, s25
	s_lshl_b32 s0, s28, 11
	s_and_b32 s30, s0, 0xe000
	s_lshl_b32 s0, s29, 5
	s_ashr_i32 s1, s0, 31
	s_add_u32 s0, s0, s30
	s_addc_u32 s1, s1, 0
	v_mov_b32_e32 v195, s1
	v_or_b32_e32 v194, s0, v172
	v_lshlrev_b64 v[2:3], 12, v[194:195]
	s_lshl_b32 s28, s27, 6
	s_lshl_b32 s92, s27, 7
	v_readfirstlane_b32 s27, v170
	v_lshl_add_u64 v[2:3], s[80:81], 0, v[2:3]
	s_ashr_i32 s34, s27, 8
	v_lshl_add_u64 v[2:3], v[2:3], 0, s[92:93]
	v_lshlrev_b32_e32 v0, 1, v174
	s_lshl_b32 s0, s34, 5
	v_lshl_add_u64 v[2:3], v[2:3], 0, v[0:1]
	s_ashr_i32 s1, s0, 31
	v_or_b32_e32 v0, s30, v177
	global_load_dwordx4 v[130:133], v[2:3], off offset:2048
	global_load_dwordx4 v[134:137], v[2:3], off offset:2080
	global_load_dwordx4 v[138:141], v[2:3], off offset:2112
	global_load_dwordx4 v[142:145], v[2:3], off offset:2144
	s_ashr_i32 s31, s27, 6
	v_lshl_add_u64 v[2:3], s[0:1], 0, v[0:1]
	s_lshr_b32 s27, s27, 2
	v_lshlrev_b64 v[2:3], 12, v[2:3]
	v_and_or_b32 v4, s27, 32, v172
	v_lshl_add_u64 v[2:3], s[80:81], 0, v[2:3]
	s_and_b32 s35, s31, 3
	v_or_b32_e32 v4, s28, v4
	v_lshl_add_u64 v[2:3], v[2:3], 0, s[92:93]
	s_lshl_b32 s92, s35, 5
	v_lshlrev_b32_e32 v4, 17, v4
	v_mov_b32_e32 v5, v1
	v_lshl_add_u64 v[2:3], v[2:3], 0, s[92:93]
	v_lshl_add_u64 v[4:5], s[4:5], 0, v[4:5]
	s_lshl_b32 s92, s30, 1
	v_lshl_add_u64 v[4:5], v[4:5], 0, s[92:93]
	s_lshl_b32 s34, s34, 13
	s_lshl_b32 s35, s35, 10
	v_lshl_add_u64 v[4:5], s[0:1], 1, v[4:5]
	s_lshl_b32 s0, s31, 5
	v_lshlrev_b32_e32 v0, 1, v176
	s_or_b32 s34, s35, s34
	s_and_b32 s92, s0, 32
	v_lshl_add_u64 v[196:197], v[2:3], 0, v[0:1]
	v_lshl_add_u64 v[4:5], v[4:5], 0, s[92:93]
	s_add_i32 s76, s34, 0
	v_lshl_add_u64 v[2:3], v[196:197], 0, s[14:15]
	v_lshl_add_u64 v[4:5], v[4:5], 0, v[0:1]
	s_mov_b64 s[0:1], 0x4000000
	s_add_i32 m0, s76, 0x8900
	v_lshl_add_u64 v[198:199], v[4:5], 0, s[0:1]
	global_load_lds_dwordx4 v[2:3], off
	s_add_i32 m0, s76, 0x9900
	s_mov_b64 s[0:1], 0x40a00
	global_load_lds_dwordx4 v[198:199], off
	v_lshl_add_u64 v[2:3], v[196:197], 0, s[0:1]
	s_add_i32 m0, s76, 0xc900
	s_mov_b64 s[0:1], 0x4000080
	global_load_lds_dwordx4 v[2:3], off
	v_lshl_add_u64 v[2:3], v[4:5], 0, s[0:1]
	s_add_i32 m0, s76, 0xd900
	s_lshl_b32 s0, s19, 2
	global_load_lds_dwordx4 v[2:3], off
	s_mov_b64 s[0:1], 0x80a00
	v_lshl_add_u64 v[2:3], v[196:197], 0, s[0:1]
	s_add_i32 m0, s76, 0x10900
	s_mov_b64 s[0:1], 0x100
	global_load_lds_dwordx4 v[2:3], off
	v_lshl_add_u64 v[2:3], v[198:199], 0, s[0:1]
	s_add_i32 m0, s76, 0x11900
	s_mov_b64 s[0:1], 0xc0a00
	global_load_lds_dwordx4 v[2:3], off
	v_lshl_add_u64 v[2:3], v[196:197], 0, s[0:1]
	s_add_i32 m0, s76, 0x14900
	s_mov_b64 s[0:1], 0x180
	global_load_lds_dwordx4 v[2:3], off
	v_lshl_add_u64 v[2:3], v[198:199], 0, s[0:1]
	s_add_i32 m0, s76, 0x15900
	s_lshl_b32 s0, s19, 2
	global_load_lds_dwordx4 v[2:3], off
	s_waitcnt vmcnt(12)
	s_mov_b64 s[56:57], exec
	s_and_b64 exec, s[56:57], s[42:43]
	ds_write_b128 v203, v[22:25]
	s_and_b64 exec, s[56:57], s[44:45]
	ds_write_b128 v203, v[6:9] offset:8192
	s_and_b64 exec, s[56:57], s[46:47]
	ds_write_b128 v203, v[10:13] offset:16384
	s_and_b64 exec, s[56:57], s[48:49]
	ds_write_b128 v203, v[14:17] offset:24576
	s_and_b64 exec, s[56:57], s[50:51]
	ds_write_b128 v203, v[18:21] offset:32768
	s_mov_b64 exec, s[56:57]
	s_waitcnt vmcnt(6) lgkmcnt(0)
	s_barrier
	v_mov_b32_e32 v16, v1
	v_mov_b32_e32 v17, v1
	s_or_b32 s78, s0, 3
	s_lshl_b32 s0, s18, 2
	v_mov_b32_e32 v0, v1
	v_mov_b32_e32 v2, v1
	v_mov_b32_e32 v3, v1
	v_mov_b32_e32 v4, v1
	v_mov_b32_e32 v5, v1
	v_mov_b32_e32 v6, v1
	v_mov_b32_e32 v7, v1
	v_mov_b32_e32 v8, v1
	v_mov_b32_e32 v9, v1
	v_mov_b32_e32 v10, v1
	v_mov_b32_e32 v11, v1
	v_mov_b32_e32 v12, v1
	v_mov_b32_e32 v13, v1
	v_mov_b32_e32 v14, v1
	v_mov_b32_e32 v15, v1
	v_mov_b64_e32 v[32:33], v[16:17]
	v_mov_b64_e32 v[64:65], v[16:17]
	v_mov_b64_e32 v[48:49], v[16:17]
	s_mov_b32 s77, 4
	s_mov_b32 s55, s54
	s_mov_b32 s56, s54
	s_mov_b32 s57, s54
	s_mov_b32 s58, s54
	s_mov_b32 s59, s54
	s_mov_b32 s60, s54
	s_mov_b32 s61, s54
	s_mov_b32 s62, s54
	s_mov_b32 s63, s54
	s_mov_b32 s64, s54
	s_mov_b32 s65, s54
	s_mov_b32 s66, s54
	s_mov_b32 s67, s54
	s_mov_b32 s68, s54
	s_mov_b32 s69, s54
	s_mov_b32 s70, s54
	s_mov_b32 s71, s54
	s_mov_b32 s79, 0
	s_sub_i32 s82, 0, s0
	v_lshl_add_u32 v206, s18, 10, v205
	s_mov_b64 s[18:19], 0
	s_movk_i32 s83, 0xff80
	s_mov_b32 s30, s29
	s_mov_b32 s31, 0
	v_mov_b64_e32 v[30:31], v[14:15]
	v_mov_b64_e32 v[28:29], v[12:13]
	v_mov_b64_e32 v[26:27], v[10:11]
	v_mov_b64_e32 v[24:25], v[8:9]
	v_mov_b64_e32 v[22:23], v[6:7]
	v_mov_b64_e32 v[20:21], v[4:5]
	v_mov_b64_e32 v[18:19], v[2:3]
	v_mov_b64_e32 v[62:63], v[14:15]
	v_mov_b64_e32 v[60:61], v[12:13]
	v_mov_b64_e32 v[58:59], v[10:11]
	v_mov_b64_e32 v[56:57], v[8:9]
	v_mov_b64_e32 v[54:55], v[6:7]
	v_mov_b64_e32 v[52:53], v[4:5]
	v_mov_b64_e32 v[50:51], v[2:3]
	v_mov_b64_e32 v[46:47], v[14:15]
	v_mov_b64_e32 v[44:45], v[12:13]
	v_mov_b64_e32 v[42:43], v[10:11]
	v_mov_b64_e32 v[40:41], v[8:9]
	v_mov_b64_e32 v[38:39], v[6:7]
	v_mov_b64_e32 v[36:37], v[4:5]
	v_mov_b64_e32 v[34:35], v[2:3]
	v_mov_b64_e32 v[200:201], v[0:1]
	s_waitcnt vmcnt(6)
	s_branch .LBB0_356

.LBB0_383:
	s_and_b64 vcc, exec, s[0:1]
	s_cbranch_vccz .LBB0_394
	s_and_b32 s27, s28, 7
	s_mul_i32 s0, s27, 0x8900
	v_readlane_b32 s1, v251, 2
	s_add_u32 s0, s1, s0
	v_readlane_b32 s1, v251, 3
	s_addc_u32 s1, s1, 0
	s_mov_b64 s[18:19], exec
	s_and_b64 exec, s[18:19], s[42:43]
	v_lshl_add_u64 v[22:23], v[170:171], 4, s[0:1]
	global_load_dwordx4 v[22:25], v[22:23], off
	s_and_b64 exec, s[18:19], s[44:45]
	v_lshl_add_u64 v[6:7], v[180:181], 4, s[0:1]
	global_load_dwordx4 v[6:9], v[6:7], off
	s_and_b64 exec, s[18:19], s[46:47]
	v_lshl_add_u64 v[10:11], v[182:183], 4, s[0:1]
	global_load_dwordx4 v[10:13], v[10:11], off
	s_and_b64 exec, s[18:19], s[48:49]
	v_lshl_add_u64 v[14:15], v[184:185], 4, s[0:1]
	global_load_dwordx4 v[14:17], v[14:15], off
	s_and_b64 exec, s[18:19], s[50:51]
	s_cbranch_execz .Lattn_a_tskip
	v_lshl_add_u64 v[18:19], v[186:187], 4, s[0:1]
	global_load_dwordx4 v[18:21], v[18:19], off
.Lattn_a_tskip:
	s_mov_b64 exec, s[18:19]
	s_branch .LBB0_405

; #define LAS __attribute__((address_space(3)))
; #define WAITBAR2() asm volatile("s_waitcnt vmcnt(2) lgkmcnt(0)\n\ts_barrier" ::: "memory")
; #define ISSUE_UP() do { STG_ISSUE(s_iss < sb_end ? s_iss : sb_end, slot_i); ++s_iss; slot_i = slot_i == NSTG - 1 ? 0 : slot_i + 1; } while (0)
; __device__ __forceinline__ void blk_A(int b, int hd, int chunk  , const bf16_t* QK, const bf16_t* VT, bf16_t* mixed, LAS unsigned char* lds, const float* tblg, int tid, int lane, int wave) {
;     const int q = lane & 31, h = lane >> 5, qbA = chunk * 16 + wave, qbB = qbA + 8;
;     LOAD_HEAD_TABLE(hd);
;     const size_t tok0 = (size_t)b * SEQ;
;     bf16x8 qfA[4], qfB[4];
;     { const bf16_t* Qp = QK + (tok0 + qbA * 32 + q) * 2048 + hd * 64 + 8 * h;
; #pragma unroll
;       for (int s = 0; s < 4; ++s) { qfA[s] = *(const bf16x8*)(Qp + 16 * s); qfB[s] = *(const bf16x8*)(Qp + (size_t)8 * 32 * 2048 + 16 * s); } }
;     const Stage st = make_stage(tid, QK, VT, tok0, 512 + hd * 64, hd * 64);
;     LAS unsigned char* sb = lds + SBUF_OFF;
;     const int sb_end = chunk * 8 + 7, sb_lo = chunk * 8 > 32 ? chunk * 8 - 32 : 0;
;     int s_iss = sb_lo, slot_i = 0, slot_c = 0;
;     ...
;     ISSUE_UP(); ISSUE_UP();
;     WAITBAR2();
;     f32x16 oA0 = {}, oA1 = {}, oB0 = {}, oB1 = {}; float lA = 0.f, lB = 0.f;
;     const LAS unsigned char* tb = LANE_TBL();
.LBB0_405:
	s_add_i32 s1, s28, 0xfffffc00
	s_lshr_b32 s0, s1, 6
	s_sub_i32 s31, 15, s0
	s_lshl_b32 s30, s31, 4
	s_add_i32 s30, s30, s25
	s_lshl_b32 s18, s28, 10
	s_and_b32 s34, s18, 0xe000
	s_lshl_b32 s18, s30, 5
	s_ashr_i32 s19, s18, 31
	s_add_u32 s18, s18, s34
	s_addc_u32 s19, s19, 0
	v_mov_b32_e32 v149, s19
	v_or_b32_e32 v148, s18, v172
	v_lshlrev_b64 v[2:3], 12, v[148:149]
	v_lshl_add_u64 v[2:3], s[80:81], 0, v[2:3]
	s_lshl_b32 s92, s27, 7
	s_lshl_b32 s29, s27, 6
	v_lshl_add_u64 v[2:3], v[2:3], 0, s[92:93]
	v_lshlrev_b32_e32 v0, 1, v174
	v_readfirstlane_b32 s27, v170
	v_lshl_add_u64 v[2:3], v[2:3], 0, v[0:1]
	s_mov_b32 s18, 0x100000
	s_ashr_i32 s52, s27, 8
	v_add_co_u32_e32 v4, vcc, s18, v2
	s_lshl_b32 s18, s52, 5
	s_ashr_i32 s19, s18, 31
	v_or_b32_e32 v0, s34, v177
	v_addc_co_u32_e32 v5, vcc, 0, v3, vcc
	global_load_dwordx4 v[96:99], v[2:3], off
	global_load_dwordx4 v[100:103], v[2:3], off offset:32
	global_load_dwordx4 v[104:107], v[4:5], off
	global_load_dwordx4 v[108:111], v[4:5], off offset:32
	global_load_dwordx4 v[112:115], v[2:3], off offset:64
	global_load_dwordx4 v[116:119], v[2:3], off offset:96
	global_load_dwordx4 v[120:123], v[4:5], off offset:64
	global_load_dwordx4 v[124:127], v[4:5], off offset:96
	v_lshl_add_u64 v[2:3], s[18:19], 0, v[0:1]
	s_ashr_i32 s35, s27, 6
	v_lshlrev_b64 v[2:3], 12, v[2:3]
	v_lshl_add_u64 v[2:3], s[80:81], 0, v[2:3]
	s_and_b32 s53, s35, 3
	v_lshl_add_u64 v[2:3], v[2:3], 0, s[92:93]
	s_lshl_b32 s92, s53, 5
	v_lshl_add_u64 v[2:3], v[2:3], 0, s[92:93]
	v_lshlrev_b32_e32 v0, 1, v176
	s_lshr_b32 s27, s27, 2
	v_lshl_add_u64 v[150:151], v[2:3], 0, v[0:1]
	v_and_or_b32 v2, s27, 32, v172
	v_or_b32_e32 v2, s29, v2
	v_lshlrev_b32_e32 v2, 17, v2
	v_mov_b32_e32 v3, v1
	v_lshl_add_u64 v[2:3], s[4:5], 0, v[2:3]
	s_lshl_b32 s92, s34, 1
	v_lshl_add_u64 v[2:3], v[2:3], 0, s[92:93]
	v_lshl_add_u64 v[2:3], s[18:19], 1, v[2:3]
	s_lshl_b32 s18, s35, 5
	s_lshl_b32 s52, s52, 13
	s_lshl_b32 s53, s53, 10
	s_and_b32 s92, s18, 32
	s_lshl_b32 s18, s31, 3
	s_or_b32 s52, s53, s52
	s_or_b32 s27, s18, 7
	s_sub_i32 s18, s18, 32
	s_cmpk_lt_u32 s1, 0x2c0
	s_cselect_b32 s1, s18, 0
	v_lshl_add_u64 v[2:3], v[2:3], 0, s[92:93]
	s_min_i32 s92, s1, s27
	s_lshl_b64 s[18:19], s[92:93], 18
	v_lshl_add_u64 v[152:153], v[2:3], 0, v[0:1]
	v_lshl_add_u64 v[2:3], v[150:151], 0, s[18:19]
	s_add_i32 s31, s52, 0
	v_lshl_add_u64 v[2:3], v[2:3], 0, s[12:13]
	s_add_i32 m0, s31, 0x8900
	s_lshl_b32 s92, s92, 7
	s_or_b32 s18, s1, 1
	global_load_lds_dwordx4 v[2:3], off
	v_lshl_add_u64 v[2:3], v[152:153], 0, s[92:93]
	s_min_i32 s92, s18, s27
	s_add_i32 m0, s31, 0x9900
	s_lshl_b64 s[18:19], s[92:93], 18
	global_load_lds_dwordx4 v[2:3], off
	v_lshl_add_u64 v[2:3], v[150:151], 0, s[18:19]
	v_lshl_add_u64 v[2:3], v[2:3], 0, s[12:13]
	s_add_i32 m0, s31, 0xc900
	s_lshl_b32 s92, s92, 7
	global_load_lds_dwordx4 v[2:3], off
	s_waitcnt vmcnt(11)
	s_mov_b64 s[56:57], exec
	s_and_b64 exec, s[56:57], s[42:43]
	ds_write_b128 v203, v[22:25]
	s_and_b64 exec, s[56:57], s[44:45]
	ds_write_b128 v203, v[6:9] offset:8192
	s_and_b64 exec, s[56:57], s[46:47]
	ds_write_b128 v203, v[10:13] offset:16384
	s_and_b64 exec, s[56:57], s[48:49]
	ds_write_b128 v203, v[14:17] offset:24576
	s_and_b64 exec, s[56:57], s[50:51]
	ds_write_b128 v203, v[18:21] offset:32768
	s_mov_b64 exec, s[56:57]
	v_lshl_add_u64 v[2:3], v[152:153], 0, s[92:93]
	s_add_i32 m0, s31, 0xd900
	s_cmp_gt_i32 s1, s27
	global_load_lds_dwordx4 v[2:3], off
	s_waitcnt vmcnt(2) lgkmcnt(0)
	s_barrier
	s_cbranch_scc1 .LBB0_419
	s_or_b32 s54, s1, 2
	s_lshl_b32 s52, s1, 1
	s_lshl_b32 s0, s0, 11
	s_lshl_b32 s1, s1, 8
	v_mov_b32_e32 v14, v1
	v_mov_b32_e32 v15, v1
	s_add_i32 s0, s0, s1
	v_mov_b32_e32 v0, v1
	v_mov_b32_e32 v2, v1
	v_mov_b32_e32 v3, v1
	v_mov_b32_e32 v4, v1
	v_mov_b32_e32 v5, v1
	v_mov_b32_e32 v6, v1
	v_mov_b32_e32 v7, v1
	v_mov_b32_e32 v8, v1
	v_mov_b32_e32 v9, v1
	v_mov_b32_e32 v10, v1
	v_mov_b32_e32 v11, v1
	v_mov_b32_e32 v12, v1
	v_mov_b32_e32 v13, v1
	v_mov_b64_e32 v[30:31], v[14:15]
	v_mov_b64_e32 v[46:47], v[14:15]
	v_mov_b64_e32 v[62:63], v[14:15]
	v_mov_b64_e32 v[78:79], v[14:15]
	s_add_i32 s34, s30, 8
	s_mov_b32 s35, 2
	v_add_u32_e32 v154, s0, v205
	s_mov_b32 s53, 0
	v_mov_b32_e32 v156, 0
	v_mov_b32_e32 v155, 0
	v_mov_b64_e32 v[28:29], v[12:13]
	v_mov_b64_e32 v[26:27], v[10:11]
	v_mov_b64_e32 v[24:25], v[8:9]
	v_mov_b64_e32 v[22:23], v[6:7]
	v_mov_b64_e32 v[20:21], v[4:5]
	v_mov_b64_e32 v[18:19], v[2:3]
	v_mov_b64_e32 v[16:17], v[0:1]
	v_mov_b64_e32 v[44:45], v[12:13]
	v_mov_b64_e32 v[42:43], v[10:11]
	v_mov_b64_e32 v[40:41], v[8:9]
	v_mov_b64_e32 v[38:39], v[6:7]
	v_mov_b64_e32 v[36:37], v[4:5]
	v_mov_b64_e32 v[34:35], v[2:3]
	v_mov_b64_e32 v[32:33], v[0:1]
	v_mov_b64_e32 v[60:61], v[12:13]
	v_mov_b64_e32 v[58:59], v[10:11]
	v_mov_b64_e32 v[56:57], v[8:9]
	v_mov_b64_e32 v[54:55], v[6:7]
	v_mov_b64_e32 v[52:53], v[4:5]
	v_mov_b64_e32 v[50:51], v[2:3]
	v_mov_b64_e32 v[48:49], v[0:1]
	v_mov_b64_e32 v[76:77], v[12:13]
	v_mov_b64_e32 v[74:75], v[10:11]
	v_mov_b64_e32 v[72:73], v[8:9]
	v_mov_b64_e32 v[70:71], v[6:7]
	v_mov_b64_e32 v[68:69], v[4:5]
	v_mov_b64_e32 v[66:67], v[2:3]
	v_mov_b64_e32 v[64:65], v[0:1]
	s_waitcnt vmcnt(2)
